# lru_item: 19 conv-window loads issued together from clamped rows (one wait) instead of 19 guarded, individually waited loads; t<0 taps zeroed afterwards
# speedup vs baseline: 1.0249x; 1.0138x over previous
; #define LAS __attribute__((address_space(3)))
; __device__ __forceinline__ void lds_barrier() { asm volatile("s_waitcnt lgkmcnt(0)" ::: "memory"); __builtin_amdgcn_s_barrier(); asm volatile("" ::: "memory"); }
; __device__ __forceinline__ int opaque_bid() { int t = blockIdx.x; asm volatile("" : "+s"(t)); return t; }
; __device__ __forceinline__ int opaque_gd() { int t = gridDim.x; asm volatile("" : "+s"(t)); return t; }
; __device__ __forceinline__ int opaque_tid() { int t = threadIdx.x; asm volatile("" : "+v"(t)); return t; }
; __device__ __forceinline__ Params fetchP(const LAS Params* lp0) { unsigned la = (unsigned)(unsigned long long)lp0; asm volatile("" : "+v"(la)); const LAS Params* lp = (const LAS Params*)la; Params q; PFIELDS(PFETCH) q.ph_lo = 0; q.ph_hi = 0; return q; }
; __device__ __forceinline__ void lru_item(const Params& p, int l, int item, LAS unsigned char* lds) {
;     const int tid = opaque_tid(), wid = tid >> 6, lane = tid & 63, fr = lane & 15, fq = lane >> 4;
;     const int b = item >> 6, h = (item >> 4) & 3, seg = item & 15;
;     LAS unsigned char* wb = lds + wid * 10752;
;     LAS bf16_t* xa = (LAS bf16_t*)wb; LAS float* xf = (LAS float*)(wb + 2304); LAS float* sa = (LAS float*)(wb + 6528);
;     LAS float* ct = (LAS float*)(lds + 86016);
;     const int t0 = seg * 128 + wid * 16; const size_t Tb = (size_t)b * SEQ;
;     const int ch = h * 64 + lane;
;     lds_barrier();
;     unsigned xr[19];
; #pragma unroll
;     for (int i = 0; i < 19; ++i) { const int t = t0 - 3 + i; xr[i] = (t >= 0) ? (unsigned)p.z[(Tb + (t >= 0 ? t : 0)) * ZLD + 2304 + ch] : 0u; }
; __device__ __forceinline__ void run_phase(const LAS Params* lp, int ph, LAS unsigned char* lds) {
;     ...
;     case 1: for (int it = opaque_bid(); it < 1280; it += opaque_gd()) { const Params p = fetchP(lp); const int jx = (it & ~255) + (it & 7) * 32 + ((it & 255) >> 3);
;             if (it < 256) hgrn_item(p, l, jx, 0, lds); else if (it < 768) attn_item(p, l, jx - 256, lds); else lru_item(p, l, jx - 768, lds); } break;
.LBB0_353:
	v_mov_b32_e32 v0, s84
	ds_read2_b64 v[4:7], v0 offset0:6 offset1:15
	ds_read2_b64 v[8:11], v0 offset0:12 offset1:13
	s_lshl_b32 s0, s2, 5
	s_and_b32 s39, s2, 0xffffff00
	s_and_b32 s95, s0, 0xe0
	s_waitcnt lgkmcnt(0)
	v_readfirstlane_b32 s26, v4
	v_readfirstlane_b32 s27, v5
	v_readfirstlane_b32 s30, v6
	v_readfirstlane_b32 s31, v7
	ds_read2_b64 v[4:7], v0 offset0:17 offset1:31
	s_or_b32 s69, s95, s39
	s_mov_b64 s[4:5], -1
	s_cmpk_gt_i32 s2, 0xff
	s_waitcnt lgkmcnt(0)
	v_readfirstlane_b32 s6, v4
	v_readfirstlane_b32 s7, v5
	v_readfirstlane_b32 s10, v6
	v_readfirstlane_b32 s11, v7
	ds_read2_b64 v[4:7], v0 offset0:34 offset1:35
	v_readfirstlane_b32 s33, v8
	v_readfirstlane_b32 s44, v9
	v_readfirstlane_b32 s17, v10
	v_readfirstlane_b32 s22, v11
	ds_read2_b64 v[8:11], v0 offset0:29 offset1:30
	s_waitcnt lgkmcnt(1)
	v_readfirstlane_b32 s70, v4
	v_readfirstlane_b32 s71, v5
	v_readfirstlane_b32 s36, v6
	v_readfirstlane_b32 s37, v7
	ds_read2_b64 v[4:7], v0 offset0:37 offset1:38
	s_waitcnt lgkmcnt(1)
	v_readfirstlane_b32 s8, v8
	v_readfirstlane_b32 s9, v9
	v_readfirstlane_b32 s15, v10
	v_readfirstlane_b32 s94, v11
	s_waitcnt lgkmcnt(0)
	v_readfirstlane_b32 s23, v4
	v_readfirstlane_b32 s97, v5
	v_readfirstlane_b32 s34, v6
	v_readfirstlane_b32 s35, v7
	ds_read2_b64 v[4:7], v0 offset0:39 offset1:40
	ds_read_b64 v[0:1], v0 offset:328
	s_waitcnt lgkmcnt(1)
	v_readfirstlane_b32 s41, v4
	v_readfirstlane_b32 s14, v5
	v_readfirstlane_b32 s20, v6
	v_readfirstlane_b32 s21, v7
	s_waitcnt lgkmcnt(0)
	v_readfirstlane_b32 s18, v0
	v_readfirstlane_b32 s19, v1
	s_cbranch_scc0 .LBB0_415
	s_bfe_u32 s96, s2, 0x50003
	s_or_b32 s42, s69, s96
	s_cmpk_gt_u32 s2, 0x2ff
	s_cbranch_scc0 .LBB0_400
	s_add_i32 s4, s69, 0xfffffd00
	v_mov_b32_e32 v1, v202
	s_bfe_u32 s38, s42, 0x20004
	s_bfe_u32 s79, s2, 0x40003
	s_ashr_i32 s28, s4, 6
	v_ashrrev_i32_e32 v0, 6, v1
	v_and_b32_e32 v3, 63, v1
	s_lshl_b32 s4, s79, 7
	s_lshl_b32 s16, s38, 6
	s_waitcnt lgkmcnt(0)
	s_barrier
	v_lshl_add_u32 v76, v0, 4, s4
	s_ashr_i32 s29, s28, 31
	v_or_b32_e32 v78, s16, v3
	s_lshl_b64 s[72:73], s[28:29], 11
	v_lshlrev_b32_e32 v4, 1, v78
	v_add_u32_e32 v5, s72, v76
	s_movk_i32 s45, 0x1600
	v_mad_u32_u24 v5, v5, s45, v4
	v_add_u32_e32 v5, 0x1200, v5
	v_add_u32_e32 v102, 0xffffbe00, v5
	v_add_u32_e32 v103, 0xffffd400, v5
	v_add_u32_e32 v104, 0xffffea00, v5
	v_mov_b32_e32 v105, v5
	v_add_u32_e32 v106, 0x1600, v5
	v_add_u32_e32 v107, 0x2c00, v5
	v_add_u32_e32 v108, 0x4200, v5
	v_add_u32_e32 v109, 0x5800, v5
	v_add_u32_e32 v110, 0x6e00, v5
	v_add_u32_e32 v111, 0x8400, v5
	v_add_u32_e32 v112, 0x9a00, v5
	v_add_u32_e32 v113, 0xb000, v5
	v_add_u32_e32 v114, 0xc600, v5
	v_add_u32_e32 v115, 0xdc00, v5
	v_add_u32_e32 v116, 0xf200, v5
	v_add_u32_e32 v117, 0x10800, v5
	v_add_u32_e32 v118, 0x11e00, v5
	v_add_u32_e32 v119, 0x13400, v5
	v_add_u32_e32 v120, 0x14a00, v5
	v_cmp_lt_i32_e32 vcc, 2, v76
	s_nop 1
	v_cndmask_b32_e32 v102, v5, v102, vcc
	v_cmp_lt_i32_e32 vcc, 1, v76
	s_nop 1
	v_cndmask_b32_e32 v103, v5, v103, vcc
	v_cmp_lt_i32_e32 vcc, 0, v76
	s_nop 1
	v_cndmask_b32_e32 v104, v5, v104, vcc
	global_load_ushort v88, v102, s[8:9]
	global_load_ushort v87, v103, s[8:9]
	global_load_ushort v85, v104, s[8:9]
	global_load_ushort v83, v105, s[8:9]
	global_load_ushort v26, v106, s[8:9]
	global_load_ushort v22, v107, s[8:9]
	global_load_ushort v24, v108, s[8:9]
	global_load_ushort v23, v109, s[8:9]
	global_load_ushort v27, v110, s[8:9]
	global_load_ushort v25, v111, s[8:9]
	global_load_ushort v82, v112, s[8:9]
	global_load_ushort v81, v113, s[8:9]
	global_load_ushort v86, v114, s[8:9]
	global_load_ushort v84, v115, s[8:9]
	global_load_ushort v90, v116, s[8:9]
	global_load_ushort v89, v117, s[8:9]
	global_load_ushort v94, v118, s[8:9]
	global_load_ushort v93, v119, s[8:9]
	global_load_ushort v95, v120, s[8:9]
	v_mov_b32_e32 v77, 0
	s_mov_b64 s[74:75], exec
	s_waitcnt vmcnt(0)
	v_lshlrev_b32_e32 v88, 16, v88
	v_lshlrev_b32_e32 v87, 16, v87
	v_lshlrev_b32_e32 v85, 16, v85
	v_lshlrev_b32_e32 v83, 16, v83
	v_lshlrev_b32_e32 v26, 16, v26
	v_lshlrev_b32_e32 v22, 16, v22
	v_lshlrev_b32_e32 v24, 16, v24
	v_lshlrev_b32_e32 v23, 16, v23
	v_lshlrev_b32_e32 v27, 16, v27
	v_lshlrev_b32_e32 v25, 16, v25
	v_lshlrev_b32_e32 v82, 16, v82
	v_lshlrev_b32_e32 v81, 16, v81
	v_lshlrev_b32_e32 v86, 16, v86
	v_lshlrev_b32_e32 v84, 16, v84
	v_lshlrev_b32_e32 v90, 16, v90
	v_lshlrev_b32_e32 v89, 16, v89
	v_lshlrev_b32_e32 v94, 16, v94
	v_lshlrev_b32_e32 v93, 16, v93
	v_lshlrev_b32_e32 v95, 16, v95
	v_cmp_lt_i32_e32 vcc, 2, v76
	s_nop 1
	v_cndmask_b32_e32 v88, 0, v88, vcc
	v_cmp_lt_i32_e32 vcc, 1, v76
	s_nop 1
	v_cndmask_b32_e32 v87, 0, v87, vcc
	v_cmp_lt_i32_e32 vcc, 0, v76
	s_nop 1
	v_cndmask_b32_e32 v85, 0, v85, vcc
